# byte-phase pinning: every GEMM K-loop head aligned to 64 bytes (.p2align 6 in front of the loop label)
# baseline (speedup 1.0000x reference)
.LBB0_157:
	s_ashr_i32 s37, s36, 31
	s_lshl_b64 s[34:35], s[36:37], 19
	s_add_u32 s38, s90, s34
	s_addc_u32 s39, s91, s35
	s_and_b64 s[34:35], s[2:3], exec
	s_cselect_b32 s5, s39, s29
	s_cselect_b32 s7, s38, s28
	s_ashr_i32 s27, s26, 31
	s_lshl_b64 s[34:35], s[26:27], 19
	s_add_u32 s40, s76, s34
	s_addc_u32 s41, s77, s35
	s_and_b64 s[34:35], s[2:3], exec
	s_cselect_b32 s27, s41, s31
	s_cselect_b32 s37, s40, s30
	s_add_u32 s28, s28, 0x40080
	s_addc_u32 s29, s29, 0
	s_add_u32 s63, s30, 0x100
	s_addc_u32 s64, s31, 0
	s_mov_b32 s65, -2
	v_mov_b32_e32 v252, 0
	v_mov_b32_e32 v253, 0
	v_mov_b32_e32 v254, 0
	v_mov_b32_e32 v255, 0
	s_nop 1
	v_mfma_f32_32x32x16_bf16 v[0:15], v[252:255], v[252:255], 0
	v_mfma_f32_32x32x16_bf16 v[16:31], v[252:255], v[252:255], 0
	v_mfma_f32_32x32x16_bf16 v[32:47], v[252:255], v[252:255], 0
	v_mfma_f32_32x32x16_bf16 v[48:63], v[252:255], v[252:255], 0
	v_mfma_f32_32x32x16_bf16 v[64:79], v[252:255], v[252:255], 0
	v_mfma_f32_32x32x16_bf16 v[80:95], v[252:255], v[252:255], 0
	v_mfma_f32_32x32x16_bf16 v[96:111], v[252:255], v[252:255], 0
	v_mfma_f32_32x32x16_bf16 v[112:127], v[252:255], v[252:255], 0
	.p2align 6

.LBB0_273:
	s_ashr_i32 s21, s20, 31
	s_lshl_b64 s[22:23], s[20:21], 18
	s_add_u32 s22, s35, s22
	s_addc_u32 s23, s36, s23
	s_and_b64 s[26:27], s[2:3], exec
	s_cselect_b32 s21, s23, s29
	s_cselect_b32 s54, s22, s28
	s_ashr_i32 s19, s18, 31
	s_lshl_b64 s[26:27], s[18:19], 19
	s_add_u32 s26, s74, s26
	s_addc_u32 s27, s75, s27
	s_and_b64 s[56:57], s[2:3], exec
	s_cselect_b32 s19, s27, s31
	s_cselect_b32 s55, s26, s30
	s_add_u32 s28, s28, 0x80
	s_addc_u32 s29, s29, 0
	s_add_u32 s56, s30, 0x100
	s_addc_u32 s57, s31, 0
	s_mov_b32 s58, -2
	v_mov_b32_e32 v252, 0
	v_mov_b32_e32 v253, 0
	v_mov_b32_e32 v254, 0
	v_mov_b32_e32 v255, 0
	s_nop 1
	v_mfma_f32_32x32x16_bf16 v[0:15], v[252:255], v[252:255], 0
	v_mfma_f32_32x32x16_bf16 v[16:31], v[252:255], v[252:255], 0
	v_mfma_f32_32x32x16_bf16 v[32:47], v[252:255], v[252:255], 0
	v_mfma_f32_32x32x16_bf16 v[48:63], v[252:255], v[252:255], 0
	.p2align 6

.LBB0_474:
	s_lshl_b32 s17, s44, 10
	s_ashr_i32 s19, s18, 31
	s_and_b32 s30, s17, 0x400
	s_lshl_b64 s[20:21], s[18:19], 19
	s_add_u32 s17, s90, s20
	s_addc_u32 s19, s91, s21
	s_add_u32 s20, s17, s30
	s_addc_u32 s21, s19, 0
	s_and_b64 s[22:23], s[2:3], exec
	s_cselect_b32 s19, s21, s27
	s_cselect_b32 s52, s20, s26
	s_ashr_i32 s17, s16, 31
	s_lshl_b64 s[22:23], s[16:17], 19
	s_add_u32 s17, s60, s22
	s_addc_u32 s23, s61, s23
	s_add_u32 s22, s17, s30
	s_addc_u32 s23, s23, 0
	s_and_b64 s[30:31], s[2:3], exec
	s_cselect_b32 s17, s23, s29
	s_cselect_b32 s53, s22, s28
	s_add_u32 s26, s26, 0x40080
	s_addc_u32 s27, s27, 0
	s_add_u32 s54, s28, 0x100
	s_addc_u32 s55, s29, 0
	s_mov_b32 s56, -2
	v_mov_b32_e32 v252, 0
	v_mov_b32_e32 v253, 0
	v_mov_b32_e32 v254, 0
	v_mov_b32_e32 v255, 0
	s_nop 1
	v_mfma_f32_32x32x16_bf16 v[0:15], v[252:255], v[252:255], 0
	v_mfma_f32_32x32x16_bf16 v[16:31], v[252:255], v[252:255], 0
	v_mfma_f32_32x32x16_bf16 v[32:47], v[252:255], v[252:255], 0
	v_mfma_f32_32x32x16_bf16 v[48:63], v[252:255], v[252:255], 0
	v_mfma_f32_32x32x16_bf16 v[64:79], v[252:255], v[252:255], 0
	v_mfma_f32_32x32x16_bf16 v[80:95], v[252:255], v[252:255], 0
	v_mfma_f32_32x32x16_bf16 v[96:111], v[252:255], v[252:255], 0
	v_mfma_f32_32x32x16_bf16 v[112:127], v[252:255], v[252:255], 0
	.p2align 6

.LBB0_492:
	s_add_i32 s56, s56, 1
	s_mul_i32 s28, s56, s86
	s_add_i32 s28, s28, s33
	s_mov_b32 s31, s67
	s_mov_b32 s30, s66
	s_and_b32 s66, s28, 3
	s_ashr_i32 s67, s28, 2
	s_cmpk_lt_i32 s28, 0x100
	s_cselect_b64 s[34:35], -1, 0
	s_and_b64 s[28:29], s[34:35], exec
	s_cselect_b32 s31, s67, s31
	s_cselect_b32 s30, s66, s30
	s_ashr_i32 s28, s31, 2
	s_ashr_i32 s29, s28, 31
	s_lshl_b64 s[28:29], s[28:29], 20
	s_add_u32 s28, s0, s28
	s_addc_u32 s29, s1, s29
	s_lshl_b32 s31, s31, 9
	s_and_b32 s40, s31, 0x600
	s_add_u32 s28, s28, s40
	s_addc_u32 s29, s29, 0
	s_ashr_i32 s31, s30, 31
	s_lshl_b64 s[30:31], s[30:31], 19
	s_add_u32 s30, s90, s30
	s_addc_u32 s31, s91, s31
	s_add_u32 s30, s30, s40
	s_addc_u32 s31, s31, 0
	v_mov_b32_e32 v127, 0
	s_and_b64 vcc, exec, s[2:3]
	v_mov_b32_e32 v126, 0
	v_mov_b32_e32 v125, 0
	v_mov_b32_e32 v124, 0
	v_mov_b32_e32 v123, 0
	v_mov_b32_e32 v122, 0
	v_mov_b32_e32 v121, 0
	v_mov_b32_e32 v120, 0
	v_mov_b32_e32 v101, 0
	v_mov_b32_e32 v100, 0
	v_mov_b32_e32 v103, 0
	v_mov_b32_e32 v102, 0
	v_mov_b32_e32 v109, 0
	v_mov_b32_e32 v108, 0
	v_mov_b32_e32 v111, 0
	v_mov_b32_e32 v110, 0
	v_mov_b32_e32 v85, 0
	v_mov_b32_e32 v84, 0
	v_mov_b32_e32 v87, 0
	v_mov_b32_e32 v86, 0
	v_mov_b32_e32 v93, 0
	v_mov_b32_e32 v92, 0
	v_mov_b32_e32 v95, 0
	v_mov_b32_e32 v94, 0
	v_mov_b32_e32 v73, 0
	v_mov_b32_e32 v72, 0
	v_mov_b32_e32 v75, 0
	v_mov_b32_e32 v74, 0
	v_mov_b32_e32 v77, 0
	v_mov_b32_e32 v76, 0
	v_mov_b32_e32 v79, 0
	v_mov_b32_e32 v78, 0
	v_mov_b32_e32 v147, 0
	v_mov_b32_e32 v146, 0
	v_mov_b32_e32 v149, 0
	v_mov_b32_e32 v148, 0
	v_mov_b32_e32 v151, 0
	v_mov_b32_e32 v150, 0
	v_mov_b32_e32 v153, 0
	v_mov_b32_e32 v152, 0
	v_mov_b32_e32 v113, 0
	v_mov_b32_e32 v112, 0
	v_mov_b32_e32 v115, 0
	v_mov_b32_e32 v114, 0
	v_mov_b32_e32 v117, 0
	v_mov_b32_e32 v116, 0
	v_mov_b32_e32 v119, 0
	v_mov_b32_e32 v118, 0
	v_mov_b32_e32 v97, 0
	v_mov_b32_e32 v96, 0
	v_mov_b32_e32 v99, 0
	v_mov_b32_e32 v98, 0
	v_mov_b32_e32 v105, 0
	v_mov_b32_e32 v104, 0
	v_mov_b32_e32 v107, 0
	v_mov_b32_e32 v106, 0
	v_mov_b32_e32 v71, 0
	v_mov_b32_e32 v70, 0
	v_mov_b32_e32 v69, 0
	v_mov_b32_e32 v68, 0
	v_mov_b32_e32 v67, 0
	v_mov_b32_e32 v66, 0
	v_mov_b32_e32 v65, 0
	v_mov_b32_e32 v64, 0
	v_mov_b32_e32 v63, 0
	v_mov_b32_e32 v62, 0
	v_mov_b32_e32 v61, 0
	v_mov_b32_e32 v60, 0
	v_mov_b32_e32 v59, 0
	v_mov_b32_e32 v58, 0
	v_mov_b32_e32 v57, 0
	v_mov_b32_e32 v56, 0
	v_mov_b32_e32 v37, 0
	v_mov_b32_e32 v36, 0
	v_mov_b32_e32 v39, 0
	v_mov_b32_e32 v38, 0
	v_mov_b32_e32 v45, 0
	v_mov_b32_e32 v44, 0
	v_mov_b32_e32 v47, 0
	v_mov_b32_e32 v46, 0
	v_mov_b32_e32 v21, 0
	v_mov_b32_e32 v20, 0
	v_mov_b32_e32 v23, 0
	v_mov_b32_e32 v22, 0
	v_mov_b32_e32 v29, 0
	v_mov_b32_e32 v28, 0
	v_mov_b32_e32 v31, 0
	v_mov_b32_e32 v30, 0
	v_mov_b32_e32 v9, 0
	v_mov_b32_e32 v8, 0
	v_mov_b32_e32 v11, 0
	v_mov_b32_e32 v10, 0
	v_mov_b32_e32 v13, 0
	v_mov_b32_e32 v12, 0
	v_mov_b32_e32 v15, 0
	v_mov_b32_e32 v14, 0
	v_mov_b32_e32 v81, 0
	v_mov_b32_e32 v80, 0
	v_mov_b32_e32 v83, 0
	v_mov_b32_e32 v82, 0
	v_mov_b32_e32 v89, 0
	v_mov_b32_e32 v88, 0
	v_mov_b32_e32 v91, 0
	v_mov_b32_e32 v90, 0
	v_mov_b32_e32 v49, 0
	v_mov_b32_e32 v48, 0
	v_mov_b32_e32 v51, 0
	v_mov_b32_e32 v50, 0
	v_mov_b32_e32 v53, 0
	v_mov_b32_e32 v52, 0
	v_mov_b32_e32 v55, 0
	v_mov_b32_e32 v54, 0
	v_mov_b32_e32 v33, 0
	v_mov_b32_e32 v32, 0
	v_mov_b32_e32 v35, 0
	v_mov_b32_e32 v34, 0
	v_mov_b32_e32 v41, 0
	v_mov_b32_e32 v40, 0
	v_mov_b32_e32 v43, 0
	v_mov_b32_e32 v42, 0
	v_mov_b32_e32 v7, 0
	v_mov_b32_e32 v6, 0
	v_mov_b32_e32 v5, 0
	v_mov_b32_e32 v4, 0
	v_mov_b32_e32 v3, 0
	v_mov_b32_e32 v2, 0
	v_mov_b32_e32 v1, 0
	v_mov_b32_e32 v0, 0
	s_cbranch_vccnz .LBB0_496
	s_and_b64 s[40:41], s[34:35], exec
	s_cselect_b32 s70, s29, s37
	s_cselect_b32 s71, s28, s36
	s_cselect_b32 s72, s31, s39
	s_cselect_b32 s73, s30, s38
	s_add_u32 s36, s36, 0x80080
	s_addc_u32 s37, s37, 0
	s_add_u32 s74, s38, 0x100
	v_mov_b32_e32 v0, 0
	s_addc_u32 s75, s39, 0
	s_mov_b32 s38, 0
	v_mov_b32_e32 v1, v0
	v_mov_b32_e32 v2, v0
	v_mov_b32_e32 v3, v0
	v_mov_b32_e32 v4, v0
	v_mov_b32_e32 v5, v0
	v_mov_b32_e32 v6, v0
	v_mov_b32_e32 v7, v0
	v_mov_b32_e32 v8, v0
	v_mov_b32_e32 v9, v0
	v_mov_b32_e32 v10, v0
	v_mov_b32_e32 v11, v0
	v_mov_b32_e32 v12, v0
	v_mov_b32_e32 v13, v0
	v_mov_b32_e32 v14, v0
	v_mov_b32_e32 v15, v0
	v_mov_b32_e32 v20, v0
	v_mov_b32_e32 v21, v0
	v_mov_b32_e32 v22, v0
	v_mov_b32_e32 v23, v0
	v_mov_b32_e32 v28, v0
	v_mov_b32_e32 v29, v0
	v_mov_b32_e32 v30, v0
	v_mov_b32_e32 v31, v0
	v_mov_b32_e32 v36, v0
	v_mov_b32_e32 v37, v0
	v_mov_b32_e32 v38, v0
	v_mov_b32_e32 v39, v0
	v_mov_b32_e32 v44, v0
	v_mov_b32_e32 v45, v0
	v_mov_b32_e32 v46, v0
	v_mov_b32_e32 v47, v0
	v_mov_b32_e32 v16, v0
	v_mov_b32_e32 v17, v0
	v_mov_b32_e32 v18, v0
	v_mov_b32_e32 v19, v0
	v_mov_b32_e32 v24, v0
	v_mov_b32_e32 v25, v0
	v_mov_b32_e32 v26, v0
	v_mov_b32_e32 v27, v0
	v_mov_b32_e32 v32, v0
	v_mov_b32_e32 v33, v0
	v_mov_b32_e32 v34, v0
	v_mov_b32_e32 v35, v0
	v_mov_b32_e32 v40, v0
	v_mov_b32_e32 v41, v0
	v_mov_b32_e32 v42, v0
	v_mov_b32_e32 v43, v0
	v_mov_b32_e32 v48, v0
	v_mov_b32_e32 v49, v0
	v_mov_b32_e32 v50, v0
	v_mov_b32_e32 v51, v0
	v_mov_b32_e32 v52, v0
	v_mov_b32_e32 v53, v0
	v_mov_b32_e32 v54, v0
	v_mov_b32_e32 v55, v0
	v_mov_b32_e32 v56, v0
	v_mov_b32_e32 v57, v0
	v_mov_b32_e32 v58, v0
	v_mov_b32_e32 v59, v0
	v_mov_b32_e32 v60, v0
	v_mov_b32_e32 v61, v0
	v_mov_b32_e32 v62, v0
	v_mov_b32_e32 v63, v0
	v_mov_b32_e32 v64, v0
	v_mov_b32_e32 v65, v0
	v_mov_b32_e32 v66, v0
	v_mov_b32_e32 v67, v0
	v_mov_b32_e32 v68, v0
	v_mov_b32_e32 v69, v0
	v_mov_b32_e32 v70, v0
	v_mov_b32_e32 v71, v0
	v_mov_b32_e32 v72, v0
	v_mov_b32_e32 v73, v0
	v_mov_b32_e32 v74, v0
	v_mov_b32_e32 v75, v0
	v_mov_b32_e32 v76, v0
	v_mov_b32_e32 v77, v0
	v_mov_b32_e32 v78, v0
	v_mov_b32_e32 v79, v0
	v_mov_b32_e32 v84, v0
	v_mov_b32_e32 v85, v0
	v_mov_b32_e32 v86, v0
	v_mov_b32_e32 v87, v0
	v_mov_b32_e32 v92, v0
	v_mov_b32_e32 v93, v0
	v_mov_b32_e32 v94, v0
	v_mov_b32_e32 v95, v0
	v_mov_b32_e32 v100, v0
	v_mov_b32_e32 v101, v0
	v_mov_b32_e32 v102, v0
	v_mov_b32_e32 v103, v0
	v_mov_b32_e32 v108, v0
	v_mov_b32_e32 v109, v0
	v_mov_b32_e32 v110, v0
	v_mov_b32_e32 v111, v0
	v_mov_b32_e32 v80, v0
	v_mov_b32_e32 v81, v0
	v_mov_b32_e32 v82, v0
	v_mov_b32_e32 v83, v0
	v_mov_b32_e32 v88, v0
	v_mov_b32_e32 v89, v0
	v_mov_b32_e32 v90, v0
	v_mov_b32_e32 v91, v0
	v_mov_b32_e32 v96, v0
	v_mov_b32_e32 v97, v0
	v_mov_b32_e32 v98, v0
	v_mov_b32_e32 v99, v0
	v_mov_b32_e32 v104, v0
	v_mov_b32_e32 v105, v0
	v_mov_b32_e32 v106, v0
	v_mov_b32_e32 v107, v0
	v_mov_b32_e32 v112, v0
	v_mov_b32_e32 v113, v0
	v_mov_b32_e32 v114, v0
	v_mov_b32_e32 v115, v0
	v_mov_b32_e32 v116, v0
	v_mov_b32_e32 v117, v0
	v_mov_b32_e32 v118, v0
	v_mov_b32_e32 v119, v0
	v_mov_b32_e32 v120, v0
	v_mov_b32_e32 v121, v0
	v_mov_b32_e32 v122, v0
	v_mov_b32_e32 v123, v0
	v_mov_b32_e32 v124, v0
	v_mov_b32_e32 v125, v0
	v_mov_b32_e32 v126, v0
	v_mov_b32_e32 v127, v0
	.p2align 6

.LBB0_508:
	s_add_i32 s54, s54, 1
	s_mul_i32 s26, s54, s86
	s_add_i32 s26, s26, s33
	s_mov_b32 s28, s65
	s_mov_b32 s29, s64
	s_and_b32 s64, s26, 3
	s_ashr_i32 s65, s26, 2
	s_cmpk_lt_i32 s26, 0x100
	s_cselect_b64 s[30:31], -1, 0
	s_and_b64 s[26:27], s[30:31], exec
	s_cselect_b32 s26, s64, s29
	s_cselect_b32 s38, s65, s28
	s_lshl_b32 s26, s26, 8
	s_lshl_b32 s28, s38, 19
	s_ashr_i32 s27, s26, 31
	s_and_b32 s28, s28, 0x180000
	s_add_u32 s39, s76, s28
	s_addc_u32 s66, s77, 0
	s_lshl_b64 s[28:29], s[26:27], 1
	s_add_u32 s26, s39, s28
	s_addc_u32 s27, s66, s29
	s_ashr_i32 s38, s38, 2
	s_ashr_i32 s39, s38, 31
	s_lshl_b64 s[38:39], s[38:39], 20
	s_add_u32 s38, s0, s38
	s_addc_u32 s39, s1, s39
	s_add_u32 s28, s38, s28
	s_addc_u32 s29, s39, s29
	s_add_u32 s28, s28, 0x800
	v_mov_b32_e32 v127, 0
	s_addc_u32 s29, s29, 0
	s_and_b64 vcc, exec, s[2:3]
	v_mov_b32_e32 v126, v127
	v_mov_b32_e32 v125, v127
	v_mov_b32_e32 v124, v127
	v_mov_b32_e32 v123, v127
	v_mov_b32_e32 v122, v127
	v_mov_b32_e32 v121, v127
	v_mov_b32_e32 v120, v127
	v_mov_b32_e32 v111, v127
	v_mov_b32_e32 v110, v127
	v_mov_b32_e32 v109, v127
	v_mov_b32_e32 v108, v127
	v_mov_b32_e32 v107, v127
	v_mov_b32_e32 v106, v127
	v_mov_b32_e32 v105, v127
	v_mov_b32_e32 v104, v127
	v_mov_b32_e32 v95, v127
	v_mov_b32_e32 v94, v127
	v_mov_b32_e32 v93, v127
	v_mov_b32_e32 v92, v127
	v_mov_b32_e32 v91, v127
	v_mov_b32_e32 v90, v127
	v_mov_b32_e32 v89, v127
	v_mov_b32_e32 v88, v127
	v_mov_b32_e32 v79, v127
	v_mov_b32_e32 v78, v127
	v_mov_b32_e32 v77, v127
	v_mov_b32_e32 v76, v127
	v_mov_b32_e32 v75, v127
	v_mov_b32_e32 v74, v127
	v_mov_b32_e32 v73, v127
	v_mov_b32_e32 v72, v127
	v_mov_b32_e32 v119, v127
	v_mov_b32_e32 v118, v127
	v_mov_b32_e32 v117, v127
	v_mov_b32_e32 v116, v127
	v_mov_b32_e32 v115, v127
	v_mov_b32_e32 v114, v127
	v_mov_b32_e32 v113, v127
	v_mov_b32_e32 v112, v127
	v_mov_b32_e32 v103, v127
	v_mov_b32_e32 v102, v127
	v_mov_b32_e32 v101, v127
	v_mov_b32_e32 v100, v127
	v_mov_b32_e32 v99, v127
	v_mov_b32_e32 v98, v127
	v_mov_b32_e32 v97, v127
	v_mov_b32_e32 v96, v127
	v_mov_b32_e32 v87, v127
	v_mov_b32_e32 v86, v127
	v_mov_b32_e32 v85, v127
	v_mov_b32_e32 v84, v127
	v_mov_b32_e32 v83, v127
	v_mov_b32_e32 v82, v127
	v_mov_b32_e32 v81, v127
	v_mov_b32_e32 v80, v127
	v_mov_b32_e32 v71, v127
	v_mov_b32_e32 v70, v127
	v_mov_b32_e32 v69, v127
	v_mov_b32_e32 v68, v127
	v_mov_b32_e32 v67, v127
	v_mov_b32_e32 v66, v127
	v_mov_b32_e32 v65, v127
	v_mov_b32_e32 v64, v127
	v_mov_b32_e32 v63, v127
	v_mov_b32_e32 v62, v127
	v_mov_b32_e32 v61, v127
	v_mov_b32_e32 v60, v127
	v_mov_b32_e32 v59, v127
	v_mov_b32_e32 v58, v127
	v_mov_b32_e32 v57, v127
	v_mov_b32_e32 v56, v127
	v_mov_b32_e32 v47, v127
	v_mov_b32_e32 v46, v127
	v_mov_b32_e32 v45, v127
	v_mov_b32_e32 v44, v127
	v_mov_b32_e32 v43, v127
	v_mov_b32_e32 v42, v127
	v_mov_b32_e32 v41, v127
	v_mov_b32_e32 v40, v127
	v_mov_b32_e32 v31, v127
	v_mov_b32_e32 v30, v127
	v_mov_b32_e32 v29, v127
	v_mov_b32_e32 v28, v127
	v_mov_b32_e32 v27, v127
	v_mov_b32_e32 v26, v127
	v_mov_b32_e32 v25, v127
	v_mov_b32_e32 v24, v127
	v_mov_b32_e32 v15, v127
	v_mov_b32_e32 v14, v127
	v_mov_b32_e32 v13, v127
	v_mov_b32_e32 v12, v127
	v_mov_b32_e32 v11, v127
	v_mov_b32_e32 v10, v127
	v_mov_b32_e32 v9, v127
	v_mov_b32_e32 v8, v127
	v_mov_b32_e32 v55, v127
	v_mov_b32_e32 v54, v127
	v_mov_b32_e32 v53, v127
	v_mov_b32_e32 v52, v127
	v_mov_b32_e32 v51, v127
	v_mov_b32_e32 v50, v127
	v_mov_b32_e32 v49, v127
	v_mov_b32_e32 v48, v127
	v_mov_b32_e32 v39, v127
	v_mov_b32_e32 v38, v127
	v_mov_b32_e32 v37, v127
	v_mov_b32_e32 v36, v127
	v_mov_b32_e32 v35, v127
	v_mov_b32_e32 v34, v127
	v_mov_b32_e32 v33, v127
	v_mov_b32_e32 v32, v127
	v_mov_b32_e32 v23, v127
	v_mov_b32_e32 v22, v127
	v_mov_b32_e32 v21, v127
	v_mov_b32_e32 v20, v127
	v_mov_b32_e32 v19, v127
	v_mov_b32_e32 v18, v127
	v_mov_b32_e32 v17, v127
	v_mov_b32_e32 v16, v127
	v_mov_b32_e32 v7, v127
	v_mov_b32_e32 v6, v127
	v_mov_b32_e32 v5, v127
	v_mov_b32_e32 v4, v127
	v_mov_b32_e32 v3, v127
	v_mov_b32_e32 v2, v127
	v_mov_b32_e32 v1, v127
	v_mov_b32_e32 v0, v127
	s_cbranch_vccnz .LBB0_511
	s_and_b64 s[38:39], s[30:31], exec
	s_cselect_b32 s66, s27, s35
	s_cselect_b32 s67, s26, s34
	s_cselect_b32 s68, s29, s37
	s_cselect_b32 s69, s28, s36
	s_add_u32 s34, s34, 0x40080
	s_addc_u32 s35, s35, 0
	s_add_u32 s70, s36, 0x100
	s_addc_u32 s71, s37, 0
	s_mov_b32 s36, 0
	v_mov_b32_e32 v252, 0
	v_mov_b32_e32 v253, 0
	v_mov_b32_e32 v254, 0
	v_mov_b32_e32 v255, 0
	s_nop 1
	v_mfma_f32_32x32x16_bf16 v[0:15], v[252:255], v[252:255], 0
	v_mfma_f32_32x32x16_bf16 v[16:31], v[252:255], v[252:255], 0
	v_mfma_f32_32x32x16_bf16 v[32:47], v[252:255], v[252:255], 0
	v_mfma_f32_32x32x16_bf16 v[48:63], v[252:255], v[252:255], 0
	v_mfma_f32_32x32x16_bf16 v[64:79], v[252:255], v[252:255], 0
	v_mfma_f32_32x32x16_bf16 v[80:95], v[252:255], v[252:255], 0
	v_mfma_f32_32x32x16_bf16 v[96:111], v[252:255], v[252:255], 0
	v_mfma_f32_32x32x16_bf16 v[112:127], v[252:255], v[252:255], 0
	.p2align 6

.LBB0_590:
	s_ashr_i32 s21, s20, 31
	s_lshl_b64 s[22:23], s[20:21], 19
	s_add_u32 s22, s10, s22
	s_addc_u32 s23, s11, s23
	s_and_b64 s[24:25], s[4:5], exec
	s_cselect_b32 s21, s23, s31
	s_cselect_b32 s27, s22, s30
	s_ashr_i32 s19, s18, 31
	s_lshl_b64 s[24:25], s[18:19], 19
	s_add_u32 s24, s62, s24
	s_addc_u32 s25, s63, s25
	s_and_b64 s[36:37], s[4:5], exec
	s_cselect_b32 s19, s25, s35
	s_cselect_b32 s55, s24, s34
	s_add_u32 s30, s30, 0x40080
	s_addc_u32 s31, s31, 0
	s_add_u32 s56, s34, 0x100
	s_addc_u32 s57, s35, 0
	s_mov_b32 s58, -2
	s_waitcnt lgkmcnt(0)
	v_mov_b32_e32 v252, 0
	v_mov_b32_e32 v253, 0
	v_mov_b32_e32 v254, 0
	v_mov_b32_e32 v255, 0
	s_nop 1
	v_mfma_f32_32x32x16_bf16 v[0:15], v[252:255], v[252:255], 0
	v_mfma_f32_32x32x16_bf16 v[16:31], v[252:255], v[252:255], 0
	v_mfma_f32_32x32x16_bf16 v[32:47], v[252:255], v[252:255], 0
	v_mfma_f32_32x32x16_bf16 v[48:63], v[252:255], v[252:255], 0
	v_mfma_f32_32x32x16_bf16 v[64:79], v[252:255], v[252:255], 0
	v_mfma_f32_32x32x16_bf16 v[80:95], v[252:255], v[252:255], 0
	v_mfma_f32_32x32x16_bf16 v[96:111], v[252:255], v[252:255], 0
	v_mfma_f32_32x32x16_bf16 v[112:127], v[252:255], v[252:255], 0
	.p2align 6

.LBB0_687:
	s_ashr_i32 s29, s28, 31
	s_lshl_b64 s[36:37], s[28:29], 19
	s_add_u32 s36, s8, s36
	s_addc_u32 s37, s9, s37
	s_and_b64 s[38:39], s[4:5], exec
	s_cselect_b32 s29, s37, s35
	s_cselect_b32 s31, s36, s34
	s_ashr_i32 s27, s26, 31
	s_lshl_b64 s[38:39], s[26:27], 19
	s_add_u32 s27, s52, s38
	s_addc_u32 s44, s53, s39
	s_ashr_i32 s38, s28, 3
	s_ashr_i32 s39, s38, 31
	s_lshl_b64 s[38:39], s[38:39], 21
	s_add_u32 s38, s27, s38
	s_addc_u32 s39, s44, s39
	s_and_b64 s[44:45], s[4:5], exec
	s_cselect_b32 s27, s39, s43
	s_cselect_b32 s70, s38, s42
	s_add_u32 s34, s34, 0x40080
	s_addc_u32 s35, s35, 0
	s_add_u32 s71, s42, 0x100
	s_addc_u32 s72, s43, 0
	s_mov_b32 s73, -2
	v_mov_b32_e32 v252, 0
	v_mov_b32_e32 v253, 0
	v_mov_b32_e32 v254, 0
	v_mov_b32_e32 v255, 0
	s_nop 1
	v_mfma_f32_32x32x16_bf16 v[0:15], v[252:255], v[252:255], 0
	v_mfma_f32_32x32x16_bf16 v[16:31], v[252:255], v[252:255], 0
	v_mfma_f32_32x32x16_bf16 v[32:47], v[252:255], v[252:255], 0
	v_mfma_f32_32x32x16_bf16 v[48:63], v[252:255], v[252:255], 0
	v_mfma_f32_32x32x16_bf16 v[64:79], v[252:255], v[252:255], 0
	v_mfma_f32_32x32x16_bf16 v[80:95], v[252:255], v[252:255], 0
	v_mfma_f32_32x32x16_bf16 v[96:111], v[252:255], v[252:255], 0
	v_mfma_f32_32x32x16_bf16 v[112:127], v[252:255], v[252:255], 0
	.p2align 6

.LBB0_802:
	s_ashr_i32 s27, s26, 31
	s_lshl_b64 s[30:31], s[26:27], 19
	s_add_u32 s30, s12, s30
	s_addc_u32 s31, s13, s31
	s_and_b64 s[0:1], s[0:1], exec
	s_cselect_b32 s25, s31, s41
	s_cselect_b32 s27, s30, s40
	s_add_u32 s0, s40, 0x40080
	s_addc_u32 s1, s41, 0
	s_add_u32 s60, s38, 0x100
	s_addc_u32 s61, s39, 0
	s_mov_b32 s62, -2
	s_waitcnt lgkmcnt(0)
	v_mov_b32_e32 v252, 0
	v_mov_b32_e32 v253, 0
	v_mov_b32_e32 v254, 0
	v_mov_b32_e32 v255, 0
	s_nop 1
	v_mfma_f32_32x32x16_bf16 v[0:15], v[252:255], v[252:255], 0
	v_mfma_f32_32x32x16_bf16 v[16:31], v[252:255], v[252:255], 0
	v_mfma_f32_32x32x16_bf16 v[32:47], v[252:255], v[252:255], 0
	v_mfma_f32_32x32x16_bf16 v[48:63], v[252:255], v[252:255], 0
	v_mfma_f32_32x32x16_bf16 v[64:79], v[252:255], v[252:255], 0
	v_mfma_f32_32x32x16_bf16 v[80:95], v[252:255], v[252:255], 0
	v_mfma_f32_32x32x16_bf16 v[96:111], v[252:255], v[252:255], 0
	v_mfma_f32_32x32x16_bf16 v[112:127], v[252:255], v[252:255], 0
	.p2align 6

.LBB0_889:
	s_ashr_i32 s21, s20, 31
	s_lshl_b64 s[22:23], s[20:21], 19
	s_add_u32 s22, s6, s22
	s_addc_u32 s23, s7, s23
	s_and_b64 s[24:25], s[2:3], exec
	s_cselect_b32 s21, s23, s29
	s_cselect_b32 s56, s22, s28
	s_ashr_i32 s19, s18, 31
	s_lshl_b64 s[24:25], s[18:19], 19
	s_add_u32 s24, s82, s24
	s_addc_u32 s25, s83, s25
	s_and_b64 s[34:35], s[2:3], exec
	s_cselect_b32 s19, s25, s31
	s_cselect_b32 s57, s24, s30
	s_add_u32 s28, s28, 0x40080
	s_addc_u32 s29, s29, 0
	s_add_u32 s58, s30, 0x100
	s_addc_u32 s59, s31, 0
	s_mov_b32 s60, -2
	v_mov_b32_e32 v252, 0
	v_mov_b32_e32 v253, 0
	v_mov_b32_e32 v254, 0
	v_mov_b32_e32 v255, 0
	s_nop 1
	v_mfma_f32_32x32x16_bf16 v[0:15], v[252:255], v[252:255], 0
	v_mfma_f32_32x32x16_bf16 v[16:31], v[252:255], v[252:255], 0
	v_mfma_f32_32x32x16_bf16 v[32:47], v[252:255], v[252:255], 0
	v_mfma_f32_32x32x16_bf16 v[48:63], v[252:255], v[252:255], 0
	v_mfma_f32_32x32x16_bf16 v[64:79], v[252:255], v[252:255], 0
	v_mfma_f32_32x32x16_bf16 v[80:95], v[252:255], v[252:255], 0
	v_mfma_f32_32x32x16_bf16 v[96:111], v[252:255], v[252:255], 0
	v_mfma_f32_32x32x16_bf16 v[112:127], v[252:255], v[252:255], 0
	.p2align 6

.LBB0_974:
	s_add_u32 s24, s24, 0xb0080
	s_addc_u32 s25, s25, 0
	s_add_u32 s54, s26, 0x100
	s_addc_u32 s55, s27, 0
	s_mov_b32 s56, -2
	s_waitcnt lgkmcnt(0)
	v_mov_b32_e32 v252, 0
	v_mov_b32_e32 v253, 0
	v_mov_b32_e32 v254, 0
	v_mov_b32_e32 v255, 0
	s_nop 1
	v_mfma_f32_32x32x16_bf16 v[0:15], v[252:255], v[252:255], 0
	v_mfma_f32_32x32x16_bf16 v[16:31], v[252:255], v[252:255], 0
	v_mfma_f32_32x32x16_bf16 v[32:47], v[252:255], v[252:255], 0
	v_mfma_f32_32x32x16_bf16 v[48:63], v[252:255], v[252:255], 0
	v_mfma_f32_32x32x16_bf16 v[64:79], v[252:255], v[252:255], 0
	v_mfma_f32_32x32x16_bf16 v[80:95], v[252:255], v[252:255], 0
	v_mfma_f32_32x32x16_bf16 v[96:111], v[252:255], v[252:255], 0
	v_mfma_f32_32x32x16_bf16 v[112:127], v[252:255], v[252:255], 0
	.p2align 6
